# guarded XCD-local barrier for the 6 row-block-local GEMM->GEMM transitions (run-time check of the workgroup->XCC mapping), on top of v26
# baseline (speedup 1.0000x reference)
.LBB0_2:
	s_or_b64 exec, exec, s[0:1]
	s_waitcnt lgkmcnt(0)
	s_barrier
	s_add_u32 s0, s72, 0x3c00000
	s_getreg_b32 s2, hwreg(HW_REG_XCC_ID, 0, 4)
	s_addc_u32 s1, s73, 0
	s_and_b32 s6, s2, 15
	s_mov_b64 s[2:3], exec
	v_readlane_b32 s4, v252, 5
	v_readlane_b32 s5, v252, 6
	s_and_b64 s[4:5], s[2:3], s[4:5]
	s_mov_b64 exec, s[4:5]
	s_cbranch_execz .LBB0_5
	s_mov_b64 s[4:5], exec
	v_mbcnt_lo_u32_b32 v1, s4, 0
	v_mbcnt_hi_u32_b32 v1, s5, v1
	v_cmp_eq_u32_e32 vcc, 0, v1
	s_and_b64 s[8:9], exec, vcc
	s_mov_b64 exec, s[8:9]
	s_cbranch_execz .LBB0_5
	s_lshl_b32 s7, s6, 8
	s_bcnt1_i32_b64 s4, s[4:5]
	v_mov_b32_e32 v1, s7
	v_mov_b32_e32 v2, s4
	global_atomic_add v1, v2, s[0:1] offset:1024
	v_readlane_b32 s7, v252, 0
	s_xor_b32 s7, s7, s6
	s_and_b32 s7, s7, 7
	s_cmp_eq_u32 s7, 0
	s_cbranch_scc1 .Lxb_map_ok
	v_mov_b32_e32 v1, 0
	v_mov_b32_e32 v2, 1
	global_atomic_add v1, v2, s[0:1] offset:256
.Lxb_map_ok:
.LBB0_5:
	s_or_b64 exec, exec, s[2:3]
	s_mov_b32 s7, 0
	v_writelane_b32 v255, s7, 40
	s_cmp_ge_i32 s74, s75
	s_cbranch_scc0 .LBB0_6
	s_getpc_b64 s[98:99]

.LBB0_1531:
	s_andn2_saveexec_b64 s[4:5], s[8:9]
	s_cbranch_execz .LBB0_1551
	s_mov_b64 s[8:9], exec
	s_lshr_b32 s4, 0x31820100, s74
	s_and_b32 s4, s4, 1
	s_cmp_lg_u32 s4, 0
	s_cbranch_scc0 .Lxb_global
	v_readlane_b32 s4, v255, 40
	s_cmp_lg_u32 s4, 0
	s_cbranch_scc1 .Lxb_have_flag
	v_readlane_b32 s4, v252, 12
	v_readlane_b32 s5, v252, 13
	v_mov_b32_e32 v0, 0
	s_nop 1
	global_load_dword v0, v0, s[4:5] offset:-256 sc1
	s_waitcnt vmcnt(0)
	v_readfirstlane_b32 s4, v0
	s_cmp_eq_u32 s4, 0
	s_cselect_b32 s4, 1, 2
	v_writelane_b32 v255, s4, 40
.Lxb_have_flag:
	s_cmp_eq_u32 s4, 1
	s_cbranch_scc1 .LBB0_1548
.Lxb_global:
	buffer_wbl2 sc1
	s_waitcnt lgkmcnt(0)
	s_waitcnt vmcnt(0)
	v_mbcnt_lo_u32_b32 v0, s8, 0
	v_mbcnt_hi_u32_b32 v0, s9, v0
	v_cmp_eq_u32_e32 vcc, 0, v0
	s_and_saveexec_b64 s[10:11], vcc
	s_cbranch_execz .LBB0_1534
	s_bcnt1_i32_b64 s4, s[8:9]
	v_mov_b32_e32 v3, s4
	v_readlane_b32 s4, v253, 12
	v_readlane_b32 s5, v253, 13
	s_nop 4
	global_atomic_add v3, v1, v3, s[4:5] sc0
